# FF1 GEMM epilogue stores made agent-scope write-through (sc1) so the phase-end L2 writeback has less to flush
# baseline (speedup 1.0000x reference)
.LBB0_32:
	s_cmp_lg_u32 s32, 0
	s_cbranch_scc1 .Lff1_cached
	v_lshlrev_b32_e32 v232, 2, v177
	v_add_u32_e32 v232, 0x20000, v232
	v_lshl_add_u32 v174, s4, 8, v177
	v_readlane_b32 s0, v249, 32
	v_or_b32_e32 v172, 16, v174
	v_ashrrev_i32_e32 v175, 31, v174
	v_readlane_b32 s1, v249, 33
	v_ashrrev_i32_e32 v173, 31, v172
	v_or_b32_e32 v170, 32, v174
	v_or_b32_e32 v168, 48, v174
	v_lshl_add_u64 v[130:131], v[174:175], 4, s[0:1]
	v_lshl_add_u64 v[132:133], v[172:173], 4, s[0:1]
	v_ashrrev_i32_e32 v171, 31, v170
	v_ashrrev_i32_e32 v169, 31, v168
	v_add_u32_e32 v166, 0x80, v174
	v_add_u32_e32 v164, 0x90, v174
	global_load_dwordx4 v[184:187], v[130:131], off
	global_load_dwordx4 v[188:191], v[132:133], off
	v_lshl_add_u64 v[130:131], v[170:171], 4, s[0:1]
	v_lshl_add_u64 v[132:133], v[168:169], 4, s[0:1]
	v_ashrrev_i32_e32 v167, 31, v166
	v_ashrrev_i32_e32 v165, 31, v164
	v_add_u32_e32 v162, 0xa0, v174
	v_add_u32_e32 v160, 0xb0, v174
	global_load_dwordx4 v[192:195], v[130:131], off
	global_load_dwordx4 v[146:149], v[132:133], off
	v_lshl_add_u64 v[130:131], v[166:167], 4, s[0:1]
	v_lshl_add_u64 v[132:133], v[164:165], 4, s[0:1]
	v_ashrrev_i32_e32 v163, 31, v162
	v_ashrrev_i32_e32 v161, 31, v160
	global_load_dwordx4 v[142:145], v[130:131], off
	global_load_dwordx4 v[138:141], v[132:133], off
	v_lshl_add_u64 v[130:131], v[162:163], 4, s[0:1]
	v_lshl_add_u64 v[132:133], v[160:161], 4, s[0:1]
	global_load_dwordx4 v[134:137], v[130:131], off
	s_nop 0
	global_load_dwordx4 v[130:133], v[132:133], off
	s_waitcnt vmcnt(0)
	v_mov_b32_e32 v196, v185
	v_mov_b32_e32 v197, v186
	v_mov_b32_e32 v185, v187
	v_pk_add_f32 v[184:185], v[196:197], v[184:185]
	s_mov_b32 s4, 0xf800000
	v_add_f32_e32 v176, v184, v185
	v_fmamk_f32 v176, v176, 0x3a800000, v234
	v_cmp_gt_f32_e32 vcc, s4, v176
	v_mul_f32_e32 v178, 0x4f800000, v176
	s_nop 0
	v_cndmask_b32_e32 v176, v176, v178, vcc
	v_sqrt_f32_e32 v178, v176
	s_nop 0
	v_add_u32_e32 v180, -1, v178
	v_fma_f32 v183, -v180, v178, v176
	v_cmp_ge_f32_e64 s[0:1], 0, v183
	v_add_u32_e32 v183, 1, v178
	s_nop 0
	v_cndmask_b32_e64 v180, v178, v180, s[0:1]
	v_fma_f32 v178, -v183, v178, v176
	v_cmp_lt_f32_e64 s[0:1], 0, v178
	s_nop 1
	v_cndmask_b32_e64 v178, v180, v183, s[0:1]
	v_mul_f32_e32 v180, 0x37800000, v178
	v_cndmask_b32_e32 v178, v178, v180, vcc
	v_cmp_class_f32_e32 vcc, v176, v235
	s_nop 1
	v_cndmask_b32_e32 v176, v178, v176, vcc
	v_div_scale_f32 v178, s[0:1], v176, v176, 1.0
	v_rcp_f32_e32 v180, v178
	s_nop 0
	v_fma_f32 v183, -v178, v180, 1.0
	v_fmac_f32_e32 v180, v183, v180
	v_div_scale_f32 v183, vcc, 1.0, v176, 1.0
	v_mul_f32_e32 v184, v183, v180
	v_fma_f32 v185, -v178, v184, v183
	v_fmac_f32_e32 v184, v185, v180
	v_fma_f32 v178, -v178, v184, v183
	v_div_fmas_f32 v178, v178, v180, v184
	v_mov_b32_e32 v184, v189
	v_mov_b32_e32 v185, v190
	v_mov_b32_e32 v189, v191
	v_pk_add_f32 v[184:185], v[184:185], v[188:189]
	v_div_fixup_f32 v176, v178, v176, 1.0
	ds_write_b32 v232, v176 offset:0
	v_add_f32_e32 v178, v184, v185
	v_fmamk_f32 v178, v178, 0x3a800000, v234
	v_cmp_gt_f32_e32 vcc, s4, v178
	v_mul_f32_e32 v180, 0x4f800000, v178
	v_pk_mul_f32 v[122:123], v[122:123], v[176:177] op_sel_hi:[1,0]
	v_cndmask_b32_e32 v178, v178, v180, vcc
	v_sqrt_f32_e32 v180, v178
	v_pk_mul_f32 v[126:127], v[126:127], v[176:177] op_sel_hi:[1,0]
	v_pk_mul_f32 v[124:125], v[124:125], v[176:177] op_sel_hi:[1,0]
	v_max_f32_e32 v122, 0, v122
	v_add_u32_e32 v183, -1, v180
	v_fma_f32 v184, -v183, v180, v178
	v_cmp_ge_f32_e64 s[0:1], 0, v184
	v_add_u32_e32 v184, 1, v180
	v_pk_mul_f32 v[128:129], v[128:129], v[176:177] op_sel_hi:[1,0]
	v_cndmask_b32_e64 v183, v180, v183, s[0:1]
	v_fma_f32 v180, -v184, v180, v178
	v_cmp_lt_f32_e64 s[0:1], 0, v180
	v_max_f32_e32 v123, 0, v123
	v_max_f32_e32 v124, 0, v124
	v_cndmask_b32_e64 v180, v183, v184, s[0:1]
	v_mul_f32_e32 v183, 0x37800000, v180
	v_cndmask_b32_e32 v180, v180, v183, vcc
	v_cmp_class_f32_e32 vcc, v178, v235
	v_max_f32_e32 v126, 0, v126
	v_max_f32_e32 v125, 0, v125
	v_cndmask_b32_e32 v178, v180, v178, vcc
	v_div_scale_f32 v180, s[0:1], v178, v178, 1.0
	v_rcp_f32_e32 v183, v180
	v_pk_mul_f32 v[116:117], v[116:117], v[176:177] op_sel_hi:[1,0]
	v_pk_mul_f32 v[114:115], v[114:115], v[176:177] op_sel_hi:[1,0]
	v_mul_f32_e32 v126, v126, v126
	v_fma_f32 v184, -v180, v183, 1.0
	v_fmac_f32_e32 v183, v184, v183
	v_div_scale_f32 v184, vcc, 1.0, v178, 1.0
	v_mul_f32_e32 v185, v184, v183
	v_fma_f32 v186, -v180, v185, v184
	v_fmac_f32_e32 v185, v186, v183
	v_fma_f32 v180, -v180, v185, v184
	v_div_fmas_f32 v180, v180, v183, v185
	v_mov_b32_e32 v184, v193
	v_mov_b32_e32 v185, v194
	v_mov_b32_e32 v193, v195
	v_pk_add_f32 v[184:185], v[184:185], v[192:193]
	v_div_fixup_f32 v178, v180, v178, 1.0
	ds_write_b32 v232, v178 offset:64
	v_add_f32_e32 v180, v184, v185
	v_fmamk_f32 v180, v180, 0x3a800000, v234
	v_cmp_gt_f32_e32 vcc, s4, v180
	v_mul_f32_e32 v183, 0x4f800000, v180
	v_mul_f32_e32 v125, v125, v125
	v_cndmask_b32_e32 v180, v180, v183, vcc
	v_sqrt_f32_e32 v183, v180
	v_pk_mul_f32 v[120:121], v[120:121], v[176:177] op_sel_hi:[1,0]
	v_pk_mul_f32 v[118:119], v[118:119], v[176:177] op_sel_hi:[1,0]
	v_max_f32_e32 v114, 0, v114
	v_add_u32_e32 v184, -1, v183
	v_fma_f32 v185, -v184, v183, v180
	v_cmp_ge_f32_e64 s[0:1], 0, v185
	v_add_u32_e32 v185, 1, v183
	v_max_f32_e32 v115, 0, v115
	v_cndmask_b32_e64 v184, v183, v184, s[0:1]
	v_fma_f32 v183, -v185, v183, v180
	v_cmp_lt_f32_e64 s[0:1], 0, v183
	v_max_f32_e32 v116, 0, v116
	v_max_f32_e32 v118, 0, v118
	v_cndmask_b32_e64 v183, v184, v185, s[0:1]
	v_mul_f32_e32 v184, 0x37800000, v183
	v_cndmask_b32_e32 v183, v183, v184, vcc
	v_cmp_class_f32_e32 vcc, v180, v235
	v_max_f32_e32 v117, 0, v117
	v_pk_mul_f32 v[106:107], v[106:107], v[178:179] op_sel_hi:[1,0]
	v_cndmask_b32_e32 v180, v183, v180, vcc
	v_div_scale_f32 v183, s[0:1], v180, v180, 1.0
	v_rcp_f32_e32 v184, v183
	v_mul_f32_e32 v118, v118, v118
	v_mul_f32_e32 v117, v117, v117
	v_pk_mul_f32 v[110:111], v[110:111], v[178:179] op_sel_hi:[1,0]
	v_fma_f32 v185, -v183, v184, 1.0
	v_fmac_f32_e32 v184, v185, v184
	v_div_scale_f32 v185, vcc, 1.0, v180, 1.0
	v_mul_f32_e32 v186, v185, v184
	v_fma_f32 v187, -v183, v186, v185
	v_fmac_f32_e32 v186, v187, v184
	v_fma_f32 v183, -v183, v186, v185
	v_div_fmas_f32 v183, v183, v184, v186
	v_mov_b32_e32 v184, v147
	v_mov_b32_e32 v185, v148
	v_mov_b32_e32 v147, v149
	v_pk_add_f32 v[146:147], v[184:185], v[146:147]
	v_div_fixup_f32 v180, v183, v180, 1.0
	ds_write_b32 v232, v180 offset:128
	v_add_f32_e32 v146, v146, v147
	v_fmamk_f32 v146, v146, 0x3a800000, v234
	v_cmp_gt_f32_e32 vcc, s4, v146
	v_mul_f32_e32 v147, 0x4f800000, v146
	v_pk_mul_f32 v[108:109], v[108:109], v[178:179] op_sel_hi:[1,0]
	v_cndmask_b32_e32 v146, v146, v147, vcc
	v_sqrt_f32_e32 v147, v146
	v_max_f32_e32 v106, 0, v106
	v_pk_mul_f32 v[112:113], v[112:113], v[178:179] op_sel_hi:[1,0]
	v_max_f32_e32 v107, 0, v107
	v_add_u32_e32 v148, -1, v147
	v_fma_f32 v149, -v148, v147, v146
	v_cmp_ge_f32_e64 s[0:1], 0, v149
	v_add_u32_e32 v149, 1, v147
	v_max_f32_e32 v108, 0, v108
	v_cndmask_b32_e64 v148, v147, v148, s[0:1]
	v_fma_f32 v147, -v149, v147, v146
	v_cmp_lt_f32_e64 s[0:1], 0, v147
	v_max_f32_e32 v110, 0, v110
	v_max_f32_e32 v109, 0, v109
	v_cndmask_b32_e64 v147, v148, v149, s[0:1]
	v_mul_f32_e32 v148, 0x37800000, v147
	v_cndmask_b32_e32 v147, v147, v148, vcc
	v_cmp_class_f32_e32 vcc, v146, v235
	v_pk_mul_f32 v[100:101], v[100:101], v[178:179] op_sel_hi:[1,0]
	v_pk_mul_f32 v[98:99], v[98:99], v[178:179] op_sel_hi:[1,0]
	v_cndmask_b32_e32 v146, v147, v146, vcc
	v_div_scale_f32 v147, s[0:1], v146, v146, 1.0
	v_rcp_f32_e32 v148, v147
	v_mul_f32_e32 v110, v110, v110
	v_mul_f32_e32 v109, v109, v109
	v_pk_mul_f32 v[104:105], v[104:105], v[178:179] op_sel_hi:[1,0]
	v_fma_f32 v149, -v147, v148, 1.0
	v_fmac_f32_e32 v148, v149, v148
	v_div_scale_f32 v149, vcc, 1.0, v146, 1.0
	v_mul_f32_e32 v183, v149, v148
	v_fma_f32 v184, -v147, v183, v149
	v_fmac_f32_e32 v183, v184, v148
	v_fma_f32 v147, -v147, v183, v149
	v_div_fmas_f32 v147, v147, v148, v183
	v_mov_b32_e32 v148, v143
	v_mov_b32_e32 v149, v144
	v_mov_b32_e32 v143, v145
	v_pk_add_f32 v[142:143], v[148:149], v[142:143]
	v_div_fixup_f32 v146, v147, v146, 1.0
	ds_write_b32 v232, v146 offset:192
	v_add_f32_e32 v142, v142, v143
	v_fmamk_f32 v142, v142, 0x3a800000, v234
	v_cmp_gt_f32_e32 vcc, s4, v142
	v_mul_f32_e32 v143, 0x4f800000, v142
	v_pk_mul_f32 v[102:103], v[102:103], v[178:179] op_sel_hi:[1,0]
	v_cndmask_b32_e32 v142, v142, v143, vcc
	v_sqrt_f32_e32 v143, v142
	v_max_f32_e32 v98, 0, v98
	v_max_f32_e32 v99, 0, v99
	v_max_f32_e32 v100, 0, v100
	v_add_u32_e32 v144, -1, v143
	v_fma_f32 v145, -v144, v143, v142
	v_cmp_ge_f32_e64 s[0:1], 0, v145
	v_add_u32_e32 v145, 1, v143
	v_max_f32_e32 v102, 0, v102
	v_cndmask_b32_e64 v144, v143, v144, s[0:1]
	v_fma_f32 v143, -v145, v143, v142
	v_cmp_lt_f32_e64 s[0:1], 0, v143
	v_max_f32_e32 v101, 0, v101
	v_pk_mul_f32 v[90:91], v[90:91], v[180:181] op_sel_hi:[1,0]
	v_cndmask_b32_e64 v143, v144, v145, s[0:1]
	v_mul_f32_e32 v144, 0x37800000, v143
	v_cndmask_b32_e32 v143, v143, v144, vcc
	v_cmp_class_f32_e32 vcc, v142, v235
	v_mul_f32_e32 v102, v102, v102
	v_mul_f32_e32 v101, v101, v101
	v_cndmask_b32_e32 v142, v143, v142, vcc
	v_div_scale_f32 v143, s[0:1], v142, v142, 1.0
	v_rcp_f32_e32 v144, v143
	v_pk_mul_f32 v[94:95], v[94:95], v[180:181] op_sel_hi:[1,0]
	v_pk_mul_f32 v[92:93], v[92:93], v[180:181] op_sel_hi:[1,0]
	v_max_f32_e32 v90, 0, v90
	v_fma_f32 v145, -v143, v144, 1.0
	v_fmac_f32_e32 v144, v145, v144
	v_div_scale_f32 v145, vcc, 1.0, v142, 1.0
	v_mul_f32_e32 v147, v145, v144
	v_fma_f32 v148, -v143, v147, v145
	v_fmac_f32_e32 v147, v148, v144
	v_fma_f32 v143, -v143, v147, v145
	v_div_fmas_f32 v143, v143, v144, v147
	v_mov_b32_e32 v144, v139
	v_mov_b32_e32 v145, v140
	v_mov_b32_e32 v139, v141
	v_pk_add_f32 v[138:139], v[144:145], v[138:139]
	v_div_fixup_f32 v142, v143, v142, 1.0
	ds_write_b32 v232, v142 offset:512
	v_add_f32_e32 v138, v138, v139
	v_fmamk_f32 v138, v138, 0x3a800000, v234
	v_cmp_gt_f32_e32 vcc, s4, v138
	v_mul_f32_e32 v139, 0x4f800000, v138
	v_pk_mul_f32 v[96:97], v[96:97], v[180:181] op_sel_hi:[1,0]
	v_cndmask_b32_e32 v138, v138, v139, vcc
	v_sqrt_f32_e32 v139, v138
	v_max_f32_e32 v91, 0, v91
	v_max_f32_e32 v92, 0, v92
	v_max_f32_e32 v94, 0, v94
	v_add_u32_e32 v140, -1, v139
	v_fma_f32 v141, -v140, v139, v138
	v_cmp_ge_f32_e64 s[0:1], 0, v141
	v_add_u32_e32 v141, 1, v139
	v_max_f32_e32 v93, 0, v93
	v_cndmask_b32_e64 v140, v139, v140, s[0:1]
	v_fma_f32 v139, -v141, v139, v138
	v_cmp_lt_f32_e64 s[0:1], 0, v139
	v_pk_mul_f32 v[84:85], v[84:85], v[180:181] op_sel_hi:[1,0]
	v_pk_mul_f32 v[82:83], v[82:83], v[180:181] op_sel_hi:[1,0]
	v_cndmask_b32_e64 v139, v140, v141, s[0:1]
	v_mul_f32_e32 v140, 0x37800000, v139
	v_cndmask_b32_e32 v139, v139, v140, vcc
	v_cmp_class_f32_e32 vcc, v138, v235
	v_mul_f32_e32 v94, v94, v94
	v_mul_f32_e32 v93, v93, v93
	v_cndmask_b32_e32 v138, v139, v138, vcc
	v_div_scale_f32 v139, s[0:1], v138, v138, 1.0
	v_rcp_f32_e32 v140, v139
	v_pk_mul_f32 v[88:89], v[88:89], v[180:181] op_sel_hi:[1,0]
	v_pk_mul_f32 v[86:87], v[86:87], v[180:181] op_sel_hi:[1,0]
	v_max_f32_e32 v82, 0, v82
	v_fma_f32 v141, -v139, v140, 1.0
	v_fmac_f32_e32 v140, v141, v140
	v_div_scale_f32 v141, vcc, 1.0, v138, 1.0
	v_mul_f32_e32 v143, v141, v140
	v_fma_f32 v144, -v139, v143, v141
	v_fmac_f32_e32 v143, v144, v140
	v_fma_f32 v139, -v139, v143, v141
	v_div_fmas_f32 v139, v139, v140, v143
	v_mov_b32_e32 v140, v135
	v_mov_b32_e32 v141, v136
	v_mov_b32_e32 v135, v137
	v_pk_add_f32 v[134:135], v[140:141], v[134:135]
	v_div_fixup_f32 v138, v139, v138, 1.0
	ds_write_b32 v232, v138 offset:576
	v_add_f32_e32 v134, v134, v135
	v_fmamk_f32 v134, v134, 0x3a800000, v234
	v_cmp_gt_f32_e32 vcc, s4, v134
	v_mul_f32_e32 v135, 0x4f800000, v134
	v_max_f32_e32 v83, 0, v83
	v_cndmask_b32_e32 v134, v134, v135, vcc
	v_sqrt_f32_e32 v135, v134
	v_max_f32_e32 v84, 0, v84
	v_max_f32_e32 v86, 0, v86
	v_max_f32_e32 v85, 0, v85
	v_add_u32_e32 v136, -1, v135
	v_fma_f32 v137, -v136, v135, v134
	v_cmp_ge_f32_e64 s[0:1], 0, v137
	v_add_u32_e32 v137, 1, v135
	v_pk_mul_f32 v[74:75], v[74:75], v[146:147] op_sel_hi:[1,0]
	v_cndmask_b32_e64 v136, v135, v136, s[0:1]
	v_fma_f32 v135, -v137, v135, v134
	v_cmp_lt_f32_e64 s[0:1], 0, v135
	v_mul_f32_e32 v86, v86, v86
	v_mul_f32_e32 v85, v85, v85
	v_cndmask_b32_e64 v135, v136, v137, s[0:1]
	v_mul_f32_e32 v136, 0x37800000, v135
	v_cndmask_b32_e32 v135, v135, v136, vcc
	v_cmp_class_f32_e32 vcc, v134, v235
	v_pk_mul_f32 v[78:79], v[78:79], v[146:147] op_sel_hi:[1,0]
	v_pk_mul_f32 v[76:77], v[76:77], v[146:147] op_sel_hi:[1,0]
	v_cndmask_b32_e32 v134, v135, v134, vcc
	v_div_scale_f32 v135, s[0:1], v134, v134, 1.0
	v_rcp_f32_e32 v136, v135
	v_max_f32_e32 v74, 0, v74
	v_pk_mul_f32 v[80:81], v[80:81], v[146:147] op_sel_hi:[1,0]
	v_max_f32_e32 v75, 0, v75
	v_fma_f32 v137, -v135, v136, 1.0
	v_fmac_f32_e32 v136, v137, v136
	v_div_scale_f32 v137, vcc, 1.0, v134, 1.0
	v_mul_f32_e32 v139, v137, v136
	v_fma_f32 v140, -v135, v139, v137
	v_fmac_f32_e32 v139, v140, v136
	v_fma_f32 v135, -v135, v139, v137
	v_div_fmas_f32 v135, v135, v136, v139
	v_mov_b32_e32 v136, v131
	v_mov_b32_e32 v137, v132
	v_mov_b32_e32 v131, v133
	v_pk_add_f32 v[130:131], v[136:137], v[130:131]
	v_div_fixup_f32 v134, v135, v134, 1.0
	ds_write_b32 v232, v134 offset:640
	v_add_f32_e32 v130, v130, v131
	v_fmamk_f32 v130, v130, 0x3a800000, v234
	v_cmp_gt_f32_e32 vcc, s4, v130
	v_mul_f32_e32 v131, 0x4f800000, v130
	v_max_f32_e32 v76, 0, v76
	v_cndmask_b32_e32 v130, v130, v131, vcc
	v_sqrt_f32_e32 v131, v130
	v_max_f32_e32 v78, 0, v78
	v_max_f32_e32 v77, 0, v77
	v_pk_mul_f32 v[68:69], v[68:69], v[146:147] op_sel_hi:[1,0]
	v_add_u32_e32 v132, -1, v131
	v_fma_f32 v133, -v132, v131, v130
	v_cmp_ge_f32_e64 s[0:1], 0, v133
	v_add_u32_e32 v133, 1, v131
	v_pk_mul_f32 v[66:67], v[66:67], v[146:147] op_sel_hi:[1,0]
	v_cndmask_b32_e64 v132, v131, v132, s[0:1]
	v_fma_f32 v131, -v133, v131, v130
	v_cmp_lt_f32_e64 s[0:1], 0, v131
	v_mul_f32_e32 v78, v78, v78
	v_mul_f32_e32 v77, v77, v77
	v_cndmask_b32_e64 v131, v132, v133, s[0:1]
	v_mul_f32_e32 v132, 0x37800000, v131
	v_cndmask_b32_e32 v131, v131, v132, vcc
	v_cmp_class_f32_e32 vcc, v130, v235
	v_pk_mul_f32 v[72:73], v[72:73], v[146:147] op_sel_hi:[1,0]
	v_pk_mul_f32 v[70:71], v[70:71], v[146:147] op_sel_hi:[1,0]
	v_cndmask_b32_e32 v130, v131, v130, vcc
	v_div_scale_f32 v131, s[0:1], v130, v130, 1.0
	v_rcp_f32_e32 v132, v131
	v_readlane_b32 s0, v249, 30
	v_readlane_b32 s1, v249, 31
	v_max_f32_e32 v66, 0, v66
	v_fma_f32 v133, -v131, v132, 1.0
	v_fmac_f32_e32 v132, v133, v132
	v_div_scale_f32 v133, vcc, 1.0, v130, 1.0
	v_mul_f32_e32 v135, v133, v132
	v_fma_f32 v136, -v131, v135, v133
	v_fmac_f32_e32 v135, v136, v132
	v_fma_f32 v131, -v131, v135, v133
	v_div_fmas_f32 v131, v131, v132, v135
	v_lshl_add_u32 v132, s52, 8, v181
	v_div_fixup_f32 v130, v131, v130, 1.0
	ds_write_b32 v232, v130 offset:704
	v_ashrrev_i32_e32 v133, 31, v132
	v_lshlrev_b64 v[136:137], 13, v[174:175]
	v_mul_f32_e32 v131, v122, v122
	v_max_f32_e32 v122, 0, v127
	v_lshl_add_u64 v[136:137], s[0:1], 0, v[136:137]
	v_lshlrev_b64 v[132:133], 1, v[132:133]
	v_mul_f32_e32 v122, v122, v122
	v_mul_f32_e32 v127, v123, v123
	v_max_f32_e32 v123, 0, v128
	v_mul_f32_e32 v128, v124, v124
	v_max_f32_e32 v124, 0, v129
	v_lshl_add_u64 v[136:137], v[136:137], 0, v[132:133]
	v_mul_f32_e32 v123, v123, v123
	v_mul_f32_e32 v124, v124, v124
	v_cvt_pk_bf16_f32 v122, v126, v122
	v_cvt_pk_bf16_f32 v123, v123, v124
	v_cvt_pk_bf16_f32 v124, v131, v127
	v_cvt_pk_bf16_f32 v125, v128, v125
	global_store_dwordx4 v[136:137], v[122:125], off sc1
	v_max_f32_e32 v67, 0, v67
	v_max_f32_e32 v68, 0, v68
	v_mul_f32_e32 v122, v114, v114
	v_max_f32_e32 v114, 0, v119
	v_mul_f32_e32 v119, v115, v115
	v_max_f32_e32 v115, 0, v120
	v_mul_f32_e32 v120, v116, v116
	v_max_f32_e32 v116, 0, v121
	v_mul_f32_e32 v114, v114, v114
	v_mul_f32_e32 v115, v115, v115
	v_mul_f32_e32 v116, v116, v116
	v_cvt_pk_bf16_f32 v114, v118, v114
	v_cvt_pk_bf16_f32 v115, v115, v116
	v_cvt_pk_bf16_f32 v116, v122, v119
	v_cvt_pk_bf16_f32 v117, v120, v117
	global_store_dwordx4 v[136:137], v[114:117], off offset:256 sc1
	v_max_f32_e32 v70, 0, v70
	v_max_f32_e32 v69, 0, v69
	v_lshlrev_b64 v[114:115], 13, v[172:173]
	v_mul_f32_e32 v116, v106, v106
	v_max_f32_e32 v106, 0, v111
	v_lshl_add_u64 v[114:115], s[0:1], 0, v[114:115]
	v_mul_f32_e32 v106, v106, v106
	v_mul_f32_e32 v111, v107, v107
	v_max_f32_e32 v107, 0, v112
	v_mul_f32_e32 v112, v108, v108
	v_max_f32_e32 v108, 0, v113
	v_lshl_add_u64 v[114:115], v[114:115], 0, v[132:133]
	v_mul_f32_e32 v107, v107, v107
	v_mul_f32_e32 v108, v108, v108
	v_cvt_pk_bf16_f32 v106, v110, v106
	v_cvt_pk_bf16_f32 v107, v107, v108
	v_cvt_pk_bf16_f32 v108, v116, v111
	v_cvt_pk_bf16_f32 v109, v112, v109
	global_store_dwordx4 v[114:115], v[106:109], off sc1
	v_pk_mul_f32 v[56:57], v[56:57], v[142:143] op_sel_hi:[1,0]
	v_mul_f32_e32 v70, v70, v70
	v_mul_f32_e32 v106, v98, v98
	v_max_f32_e32 v98, 0, v103
	v_mul_f32_e32 v103, v99, v99
	v_max_f32_e32 v99, 0, v104
	v_mul_f32_e32 v104, v100, v100
	v_max_f32_e32 v100, 0, v105
	v_mul_f32_e32 v98, v98, v98
	v_mul_f32_e32 v99, v99, v99
	v_mul_f32_e32 v100, v100, v100
	v_cvt_pk_bf16_f32 v98, v102, v98
	v_cvt_pk_bf16_f32 v99, v99, v100
	v_cvt_pk_bf16_f32 v100, v106, v103
	v_cvt_pk_bf16_f32 v101, v104, v101
	global_store_dwordx4 v[114:115], v[98:101], off offset:256 sc1
	v_mul_f32_e32 v69, v69, v69
	v_pk_mul_f32 v[60:61], v[60:61], v[142:143] op_sel_hi:[1,0]
	v_lshlrev_b64 v[98:99], 13, v[170:171]
	v_mul_f32_e32 v100, v90, v90
	v_max_f32_e32 v90, 0, v95
	v_lshl_add_u64 v[98:99], s[0:1], 0, v[98:99]
	v_mul_f32_e32 v90, v90, v90
	v_mul_f32_e32 v95, v91, v91
	v_max_f32_e32 v91, 0, v96
	v_mul_f32_e32 v96, v92, v92
	v_max_f32_e32 v92, 0, v97
	v_lshl_add_u64 v[98:99], v[98:99], 0, v[132:133]
	v_mul_f32_e32 v91, v91, v91
	v_mul_f32_e32 v92, v92, v92
	v_cvt_pk_bf16_f32 v90, v94, v90
	v_cvt_pk_bf16_f32 v91, v91, v92
	v_cvt_pk_bf16_f32 v92, v100, v95
	v_cvt_pk_bf16_f32 v93, v96, v93
	global_store_dwordx4 v[98:99], v[90:93], off sc1
	v_pk_mul_f32 v[58:59], v[58:59], v[142:143] op_sel_hi:[1,0]
	v_max_f32_e32 v56, 0, v56
	v_mul_f32_e32 v90, v82, v82
	v_max_f32_e32 v82, 0, v87
	v_mul_f32_e32 v87, v83, v83
	v_max_f32_e32 v83, 0, v88
	v_mul_f32_e32 v88, v84, v84
	v_max_f32_e32 v84, 0, v89
	v_mul_f32_e32 v82, v82, v82
	v_mul_f32_e32 v83, v83, v83
	v_mul_f32_e32 v84, v84, v84
	v_cvt_pk_bf16_f32 v82, v86, v82
	v_cvt_pk_bf16_f32 v83, v83, v84
	v_cvt_pk_bf16_f32 v84, v90, v87
	v_cvt_pk_bf16_f32 v85, v88, v85
	global_store_dwordx4 v[98:99], v[82:85], off offset:256 sc1
	v_pk_mul_f32 v[62:63], v[62:63], v[142:143] op_sel_hi:[1,0]
	v_max_f32_e32 v57, 0, v57
	v_lshlrev_b64 v[82:83], 13, v[168:169]
	v_mul_f32_e32 v84, v74, v74
	v_max_f32_e32 v74, 0, v79
	v_lshl_add_u64 v[82:83], s[0:1], 0, v[82:83]
	v_mul_f32_e32 v74, v74, v74
	v_mul_f32_e32 v79, v75, v75
	v_max_f32_e32 v75, 0, v80
	v_mul_f32_e32 v80, v76, v76
	v_max_f32_e32 v76, 0, v81
	v_lshl_add_u64 v[82:83], v[82:83], 0, v[132:133]
	v_mul_f32_e32 v75, v75, v75
	v_mul_f32_e32 v76, v76, v76
	v_cvt_pk_bf16_f32 v74, v78, v74
	v_cvt_pk_bf16_f32 v75, v75, v76
	v_cvt_pk_bf16_f32 v76, v84, v79
	v_cvt_pk_bf16_f32 v77, v80, v77
	global_store_dwordx4 v[82:83], v[74:77], off sc1
	v_max_f32_e32 v58, 0, v58
	v_max_f32_e32 v60, 0, v60
	v_mul_f32_e32 v74, v66, v66
	v_max_f32_e32 v66, 0, v71
	v_mul_f32_e32 v71, v67, v67
	v_max_f32_e32 v67, 0, v72
	v_mul_f32_e32 v72, v68, v68
	v_max_f32_e32 v68, 0, v73
	v_mul_f32_e32 v66, v66, v66
	v_mul_f32_e32 v67, v67, v67
	v_mul_f32_e32 v68, v68, v68
	v_cvt_pk_bf16_f32 v66, v70, v66
	v_cvt_pk_bf16_f32 v67, v67, v68
	v_cvt_pk_bf16_f32 v68, v74, v71
	v_cvt_pk_bf16_f32 v69, v72, v69
	global_store_dwordx4 v[82:83], v[66:69], off offset:256 sc1
	v_max_f32_e32 v59, 0, v59
	v_pk_mul_f32 v[50:51], v[50:51], v[142:143] op_sel_hi:[1,0]
	v_lshlrev_b64 v[66:67], 13, v[166:167]
	v_mul_f32_e32 v68, v56, v56
	v_max_f32_e32 v56, 0, v61
	v_lshl_add_u64 v[66:67], s[0:1], 0, v[66:67]
	v_mul_f32_e32 v56, v56, v56
	v_mul_f32_e32 v61, v57, v57
	v_max_f32_e32 v57, 0, v62
	v_mul_f32_e32 v62, v58, v58
	v_max_f32_e32 v58, 0, v63
	v_pk_mul_f32 v[48:49], v[48:49], v[142:143] op_sel_hi:[1,0]
	v_lshl_add_u64 v[66:67], v[66:67], 0, v[132:133]
	v_mul_f32_e32 v60, v60, v60
	v_mul_f32_e32 v57, v57, v57
	v_mul_f32_e32 v58, v58, v58
	v_mul_f32_e32 v59, v59, v59
	v_cvt_pk_bf16_f32 v56, v60, v56
	v_pk_mul_f32 v[54:55], v[54:55], v[142:143] op_sel_hi:[1,0]
	v_pk_mul_f32 v[52:53], v[52:53], v[142:143] op_sel_hi:[1,0]
	v_max_f32_e32 v48, 0, v48
	v_max_f32_e32 v49, 0, v49
	v_max_f32_e32 v50, 0, v50
	v_cvt_pk_bf16_f32 v57, v57, v58
	v_cvt_pk_bf16_f32 v58, v68, v61
	v_cvt_pk_bf16_f32 v59, v62, v59
	global_store_dwordx4 v[66:67], v[56:59], off sc1
	v_max_f32_e32 v52, 0, v52
	v_max_f32_e32 v51, 0, v51
	v_mul_f32_e32 v56, v48, v48
	v_max_f32_e32 v48, 0, v53
	v_mul_f32_e32 v53, v49, v49
	v_max_f32_e32 v49, 0, v54
	v_mul_f32_e32 v54, v50, v50
	v_max_f32_e32 v50, 0, v55
	v_mul_f32_e32 v48, v48, v48
	v_mul_f32_e32 v49, v49, v49
	v_mul_f32_e32 v50, v50, v50
	v_pk_mul_f32 v[40:41], v[40:41], v[138:139] op_sel_hi:[1,0]
	v_mul_f32_e32 v52, v52, v52
	v_mul_f32_e32 v51, v51, v51
	v_cvt_pk_bf16_f32 v48, v52, v48
	v_cvt_pk_bf16_f32 v49, v49, v50
	v_cvt_pk_bf16_f32 v50, v56, v53
	v_pk_mul_f32 v[44:45], v[44:45], v[138:139] op_sel_hi:[1,0]
	v_pk_mul_f32 v[42:43], v[42:43], v[138:139] op_sel_hi:[1,0]
	v_max_f32_e32 v40, 0, v40
	v_cvt_pk_bf16_f32 v51, v54, v51
	global_store_dwordx4 v[66:67], v[48:51], off offset:256 sc1
	v_pk_mul_f32 v[46:47], v[46:47], v[138:139] op_sel_hi:[1,0]
	v_max_f32_e32 v41, 0, v41
	v_lshlrev_b64 v[48:49], 13, v[164:165]
	v_mul_f32_e32 v50, v40, v40
	v_max_f32_e32 v40, 0, v45
	v_max_f32_e32 v42, 0, v42
	v_lshl_add_u64 v[48:49], s[0:1], 0, v[48:49]
	v_max_f32_e32 v44, 0, v44
	v_mul_f32_e32 v40, v40, v40
	v_mul_f32_e32 v45, v41, v41
	v_max_f32_e32 v41, 0, v46
	v_mul_f32_e32 v46, v42, v42
	v_max_f32_e32 v42, 0, v47
	v_max_f32_e32 v43, 0, v43
	v_pk_mul_f32 v[34:35], v[34:35], v[138:139] op_sel_hi:[1,0]
	v_pk_mul_f32 v[32:33], v[32:33], v[138:139] op_sel_hi:[1,0]
	v_lshl_add_u64 v[48:49], v[48:49], 0, v[132:133]
	v_mul_f32_e32 v44, v44, v44
	v_mul_f32_e32 v41, v41, v41
	v_mul_f32_e32 v42, v42, v42
	v_mul_f32_e32 v43, v43, v43
	v_cvt_pk_bf16_f32 v40, v44, v40
	v_pk_mul_f32 v[38:39], v[38:39], v[138:139] op_sel_hi:[1,0]
	v_pk_mul_f32 v[36:37], v[36:37], v[138:139] op_sel_hi:[1,0]
	v_max_f32_e32 v32, 0, v32
	v_max_f32_e32 v33, 0, v33
	v_max_f32_e32 v34, 0, v34
	v_cvt_pk_bf16_f32 v41, v41, v42
	v_cvt_pk_bf16_f32 v42, v50, v45
	v_cvt_pk_bf16_f32 v43, v46, v43
	global_store_dwordx4 v[48:49], v[40:43], off sc1
	v_max_f32_e32 v36, 0, v36
	v_max_f32_e32 v35, 0, v35
	v_mul_f32_e32 v40, v32, v32
	v_max_f32_e32 v32, 0, v37
	v_mul_f32_e32 v37, v33, v33
	v_max_f32_e32 v33, 0, v38
	v_mul_f32_e32 v38, v34, v34
	v_max_f32_e32 v34, 0, v39
	v_mul_f32_e32 v32, v32, v32
	v_mul_f32_e32 v33, v33, v33
	v_mul_f32_e32 v34, v34, v34
	v_pk_mul_f32 v[24:25], v[24:25], v[134:135] op_sel_hi:[1,0]
	v_mul_f32_e32 v36, v36, v36
	v_mul_f32_e32 v35, v35, v35
	v_cvt_pk_bf16_f32 v32, v36, v32
	v_cvt_pk_bf16_f32 v33, v33, v34
	v_cvt_pk_bf16_f32 v34, v40, v37
	v_pk_mul_f32 v[28:29], v[28:29], v[134:135] op_sel_hi:[1,0]
	v_pk_mul_f32 v[26:27], v[26:27], v[134:135] op_sel_hi:[1,0]
	v_max_f32_e32 v24, 0, v24
	v_cvt_pk_bf16_f32 v35, v38, v35
	global_store_dwordx4 v[48:49], v[32:35], off offset:256 sc1
	v_pk_mul_f32 v[30:31], v[30:31], v[134:135] op_sel_hi:[1,0]
	v_max_f32_e32 v25, 0, v25
	v_lshlrev_b64 v[32:33], 13, v[162:163]
	v_mul_f32_e32 v34, v24, v24
	v_max_f32_e32 v24, 0, v29
	v_max_f32_e32 v26, 0, v26
	v_lshl_add_u64 v[32:33], s[0:1], 0, v[32:33]
	v_max_f32_e32 v28, 0, v28
	v_mul_f32_e32 v24, v24, v24
	v_mul_f32_e32 v29, v25, v25
	v_max_f32_e32 v25, 0, v30
	v_mul_f32_e32 v30, v26, v26
	v_max_f32_e32 v26, 0, v31
	v_max_f32_e32 v27, 0, v27
	v_pk_mul_f32 v[18:19], v[18:19], v[134:135] op_sel_hi:[1,0]
	v_pk_mul_f32 v[16:17], v[16:17], v[134:135] op_sel_hi:[1,0]
	v_lshl_add_u64 v[32:33], v[32:33], 0, v[132:133]
	v_mul_f32_e32 v28, v28, v28
	v_mul_f32_e32 v25, v25, v25
	v_mul_f32_e32 v26, v26, v26
	v_mul_f32_e32 v27, v27, v27
	v_cvt_pk_bf16_f32 v24, v28, v24
	v_pk_mul_f32 v[22:23], v[22:23], v[134:135] op_sel_hi:[1,0]
	v_pk_mul_f32 v[20:21], v[20:21], v[134:135] op_sel_hi:[1,0]
	v_max_f32_e32 v16, 0, v16
	v_max_f32_e32 v17, 0, v17
	v_max_f32_e32 v18, 0, v18
	v_cvt_pk_bf16_f32 v25, v25, v26
	v_cvt_pk_bf16_f32 v26, v34, v29
	v_cvt_pk_bf16_f32 v27, v30, v27
	global_store_dwordx4 v[32:33], v[24:27], off sc1
	v_max_f32_e32 v20, 0, v20
	v_max_f32_e32 v19, 0, v19
	v_mul_f32_e32 v24, v16, v16
	v_max_f32_e32 v16, 0, v21
	v_mul_f32_e32 v21, v17, v17
	v_max_f32_e32 v17, 0, v22
	v_mul_f32_e32 v22, v18, v18
	v_max_f32_e32 v18, 0, v23
	v_mul_f32_e32 v16, v16, v16
	v_mul_f32_e32 v17, v17, v17
	v_mul_f32_e32 v18, v18, v18
	v_pk_mul_f32 v[8:9], v[8:9], v[130:131] op_sel_hi:[1,0]
	v_mul_f32_e32 v20, v20, v20
	v_mul_f32_e32 v19, v19, v19
	v_cvt_pk_bf16_f32 v16, v20, v16
	v_cvt_pk_bf16_f32 v17, v17, v18
	v_cvt_pk_bf16_f32 v18, v24, v21
	v_pk_mul_f32 v[12:13], v[12:13], v[130:131] op_sel_hi:[1,0]
	v_pk_mul_f32 v[10:11], v[10:11], v[130:131] op_sel_hi:[1,0]
	v_max_f32_e32 v8, 0, v8
	v_cvt_pk_bf16_f32 v19, v22, v19
	global_store_dwordx4 v[32:33], v[16:19], off offset:256 sc1
	v_pk_mul_f32 v[14:15], v[14:15], v[130:131] op_sel_hi:[1,0]
	v_max_f32_e32 v9, 0, v9
	v_lshlrev_b64 v[16:17], 13, v[160:161]
	v_mul_f32_e32 v18, v8, v8
	v_max_f32_e32 v8, 0, v13
	v_max_f32_e32 v10, 0, v10
	v_lshl_add_u64 v[16:17], s[0:1], 0, v[16:17]
	v_max_f32_e32 v12, 0, v12
	v_mul_f32_e32 v8, v8, v8
	v_mul_f32_e32 v13, v9, v9
	v_max_f32_e32 v9, 0, v14
	v_mul_f32_e32 v14, v10, v10
	v_max_f32_e32 v10, 0, v15
	v_max_f32_e32 v11, 0, v11
	v_pk_mul_f32 v[2:3], v[2:3], v[130:131] op_sel_hi:[1,0]
	v_pk_mul_f32 v[0:1], v[0:1], v[130:131] op_sel_hi:[1,0]
	v_lshl_add_u64 v[16:17], v[16:17], 0, v[132:133]
	v_mul_f32_e32 v12, v12, v12
	v_mul_f32_e32 v9, v9, v9
	v_mul_f32_e32 v10, v10, v10
	v_mul_f32_e32 v11, v11, v11
	v_cvt_pk_bf16_f32 v8, v12, v8
	v_pk_mul_f32 v[6:7], v[6:7], v[130:131] op_sel_hi:[1,0]
	v_pk_mul_f32 v[4:5], v[4:5], v[130:131] op_sel_hi:[1,0]
	v_max_f32_e32 v0, 0, v0
	v_max_f32_e32 v1, 0, v1
	v_max_f32_e32 v2, 0, v2
	v_cvt_pk_bf16_f32 v9, v9, v10
	v_cvt_pk_bf16_f32 v10, v18, v13
	v_cvt_pk_bf16_f32 v11, v14, v11
	global_store_dwordx4 v[16:17], v[8:11], off sc1
	v_max_f32_e32 v3, 0, v3
	v_max_f32_e32 v4, 0, v4
	v_mul_f32_e32 v8, v0, v0
	v_max_f32_e32 v0, 0, v5
	v_mul_f32_e32 v5, v1, v1
	v_max_f32_e32 v1, 0, v6
	v_mul_f32_e32 v6, v2, v2
	v_max_f32_e32 v2, 0, v7
	v_mul_f32_e32 v0, v0, v0
	v_mul_f32_e32 v1, v1, v1
	v_mul_f32_e32 v2, v2, v2
	v_mul_f32_e32 v3, v3, v3
	s_mov_b64 s[0:1], -1
	s_andn2_b64 vcc, exec, s[42:43]
	v_mul_f32_e32 v4, v4, v4
	v_cvt_pk_bf16_f32 v0, v4, v0
	v_cvt_pk_bf16_f32 v1, v1, v2
	v_cvt_pk_bf16_f32 v2, v8, v5
	v_cvt_pk_bf16_f32 v3, v6, v3
	global_store_dwordx4 v[16:17], v[0:3], off offset:256 sc1
	s_mov_b32 s32, 1

.Lff1_cached:
	v_lshlrev_b32_e32 v232, 2, v177
	v_add_u32_e32 v232, 0x20000, v232
	ds_read_b32 v176, v232 offset:0
	ds_read_b32 v178, v232 offset:64
	ds_read_b32 v180, v232 offset:128
	ds_read_b32 v146, v232 offset:192
	ds_read_b32 v142, v232 offset:512
	ds_read_b32 v138, v232 offset:576
	ds_read_b32 v134, v232 offset:640
	ds_read_b32 v130, v232 offset:704
	s_waitcnt lgkmcnt(0)
	v_lshl_add_u32 v174, s4, 8, v177
	v_or_b32_e32 v172, 16, v174
	v_ashrrev_i32_e32 v175, 31, v174
	v_ashrrev_i32_e32 v173, 31, v172
	v_or_b32_e32 v170, 32, v174
	v_or_b32_e32 v168, 48, v174
	v_ashrrev_i32_e32 v171, 31, v170
	v_ashrrev_i32_e32 v169, 31, v168
	v_add_u32_e32 v166, 0x80, v174
	v_add_u32_e32 v164, 0x90, v174
	v_ashrrev_i32_e32 v167, 31, v166
	v_ashrrev_i32_e32 v165, 31, v164
	v_add_u32_e32 v162, 0xa0, v174
	v_add_u32_e32 v160, 0xb0, v174
	v_ashrrev_i32_e32 v163, 31, v162
	v_ashrrev_i32_e32 v161, 31, v160
	s_nop 0
	s_waitcnt vmcnt(0)
	s_nop 0
	s_nop 0
	s_nop 0
	s_nop 1
	s_nop 1
	s_nop 0
	v_pk_mul_f32 v[122:123], v[122:123], v[176:177] op_sel_hi:[1,0]
	v_pk_mul_f32 v[126:127], v[126:127], v[176:177] op_sel_hi:[1,0]
	v_pk_mul_f32 v[124:125], v[124:125], v[176:177] op_sel_hi:[1,0]
	v_max_f32_e32 v122, 0, v122
	v_pk_mul_f32 v[128:129], v[128:129], v[176:177] op_sel_hi:[1,0]
	v_max_f32_e32 v123, 0, v123
	v_max_f32_e32 v124, 0, v124
	v_max_f32_e32 v126, 0, v126
	v_max_f32_e32 v125, 0, v125
	v_pk_mul_f32 v[116:117], v[116:117], v[176:177] op_sel_hi:[1,0]
	v_pk_mul_f32 v[114:115], v[114:115], v[176:177] op_sel_hi:[1,0]
	v_mul_f32_e32 v126, v126, v126
	v_mul_f32_e32 v125, v125, v125
	v_pk_mul_f32 v[120:121], v[120:121], v[176:177] op_sel_hi:[1,0]
	v_pk_mul_f32 v[118:119], v[118:119], v[176:177] op_sel_hi:[1,0]
	v_max_f32_e32 v114, 0, v114
	v_max_f32_e32 v115, 0, v115
	v_max_f32_e32 v116, 0, v116
	v_max_f32_e32 v118, 0, v118
	v_max_f32_e32 v117, 0, v117
	v_pk_mul_f32 v[106:107], v[106:107], v[178:179] op_sel_hi:[1,0]
	v_mul_f32_e32 v118, v118, v118
	v_mul_f32_e32 v117, v117, v117
	v_pk_mul_f32 v[110:111], v[110:111], v[178:179] op_sel_hi:[1,0]
	v_pk_mul_f32 v[108:109], v[108:109], v[178:179] op_sel_hi:[1,0]
	v_max_f32_e32 v106, 0, v106
	v_pk_mul_f32 v[112:113], v[112:113], v[178:179] op_sel_hi:[1,0]
	v_max_f32_e32 v107, 0, v107
	v_max_f32_e32 v108, 0, v108
	v_max_f32_e32 v110, 0, v110
	v_max_f32_e32 v109, 0, v109
	v_pk_mul_f32 v[100:101], v[100:101], v[178:179] op_sel_hi:[1,0]
	v_pk_mul_f32 v[98:99], v[98:99], v[178:179] op_sel_hi:[1,0]
	v_mul_f32_e32 v110, v110, v110
	v_mul_f32_e32 v109, v109, v109
	v_pk_mul_f32 v[104:105], v[104:105], v[178:179] op_sel_hi:[1,0]
	v_pk_mul_f32 v[102:103], v[102:103], v[178:179] op_sel_hi:[1,0]
	v_max_f32_e32 v98, 0, v98
	v_max_f32_e32 v99, 0, v99
	v_max_f32_e32 v100, 0, v100
	v_max_f32_e32 v102, 0, v102
	v_max_f32_e32 v101, 0, v101
	v_pk_mul_f32 v[90:91], v[90:91], v[180:181] op_sel_hi:[1,0]
	v_mul_f32_e32 v102, v102, v102
	v_mul_f32_e32 v101, v101, v101
	v_pk_mul_f32 v[94:95], v[94:95], v[180:181] op_sel_hi:[1,0]
	v_pk_mul_f32 v[92:93], v[92:93], v[180:181] op_sel_hi:[1,0]
	v_max_f32_e32 v90, 0, v90
	v_pk_mul_f32 v[96:97], v[96:97], v[180:181] op_sel_hi:[1,0]
	v_max_f32_e32 v91, 0, v91
	v_max_f32_e32 v92, 0, v92
	v_max_f32_e32 v94, 0, v94
	v_max_f32_e32 v93, 0, v93
	v_pk_mul_f32 v[84:85], v[84:85], v[180:181] op_sel_hi:[1,0]
	v_pk_mul_f32 v[82:83], v[82:83], v[180:181] op_sel_hi:[1,0]
	v_mul_f32_e32 v94, v94, v94
	v_mul_f32_e32 v93, v93, v93
	v_pk_mul_f32 v[88:89], v[88:89], v[180:181] op_sel_hi:[1,0]
	v_pk_mul_f32 v[86:87], v[86:87], v[180:181] op_sel_hi:[1,0]
	v_max_f32_e32 v82, 0, v82
	v_max_f32_e32 v83, 0, v83
	v_max_f32_e32 v84, 0, v84
	v_max_f32_e32 v86, 0, v86
	v_max_f32_e32 v85, 0, v85
	v_pk_mul_f32 v[74:75], v[74:75], v[146:147] op_sel_hi:[1,0]
	v_mul_f32_e32 v86, v86, v86
	v_mul_f32_e32 v85, v85, v85
	v_pk_mul_f32 v[78:79], v[78:79], v[146:147] op_sel_hi:[1,0]
	v_pk_mul_f32 v[76:77], v[76:77], v[146:147] op_sel_hi:[1,0]
	v_max_f32_e32 v74, 0, v74
	v_pk_mul_f32 v[80:81], v[80:81], v[146:147] op_sel_hi:[1,0]
	v_max_f32_e32 v75, 0, v75
	v_max_f32_e32 v76, 0, v76
	v_max_f32_e32 v78, 0, v78
	v_max_f32_e32 v77, 0, v77
	v_pk_mul_f32 v[68:69], v[68:69], v[146:147] op_sel_hi:[1,0]
	v_pk_mul_f32 v[66:67], v[66:67], v[146:147] op_sel_hi:[1,0]
	v_mul_f32_e32 v78, v78, v78
	v_mul_f32_e32 v77, v77, v77
	v_pk_mul_f32 v[72:73], v[72:73], v[146:147] op_sel_hi:[1,0]
	v_pk_mul_f32 v[70:71], v[70:71], v[146:147] op_sel_hi:[1,0]
	v_readlane_b32 s0, v249, 30
	v_readlane_b32 s1, v249, 31
	v_max_f32_e32 v66, 0, v66
	v_lshl_add_u32 v132, s52, 8, v181
	v_ashrrev_i32_e32 v133, 31, v132
	v_lshlrev_b64 v[136:137], 13, v[174:175]
	v_mul_f32_e32 v131, v122, v122
	v_max_f32_e32 v122, 0, v127
	v_lshl_add_u64 v[136:137], s[0:1], 0, v[136:137]
	v_lshlrev_b64 v[132:133], 1, v[132:133]
	v_mul_f32_e32 v122, v122, v122
	v_mul_f32_e32 v127, v123, v123
	v_max_f32_e32 v123, 0, v128
	v_mul_f32_e32 v128, v124, v124
	v_max_f32_e32 v124, 0, v129
	v_lshl_add_u64 v[136:137], v[136:137], 0, v[132:133]
	v_mul_f32_e32 v123, v123, v123
	v_mul_f32_e32 v124, v124, v124
	v_cvt_pk_bf16_f32 v122, v126, v122
	v_cvt_pk_bf16_f32 v123, v123, v124
	v_cvt_pk_bf16_f32 v124, v131, v127
	v_cvt_pk_bf16_f32 v125, v128, v125
	global_store_dwordx4 v[136:137], v[122:125], off sc1
	v_max_f32_e32 v67, 0, v67
	v_max_f32_e32 v68, 0, v68
	v_mul_f32_e32 v122, v114, v114
	v_max_f32_e32 v114, 0, v119
	v_mul_f32_e32 v119, v115, v115
	v_max_f32_e32 v115, 0, v120
	v_mul_f32_e32 v120, v116, v116
	v_max_f32_e32 v116, 0, v121
	v_mul_f32_e32 v114, v114, v114
	v_mul_f32_e32 v115, v115, v115
	v_mul_f32_e32 v116, v116, v116
	v_cvt_pk_bf16_f32 v114, v118, v114
	v_cvt_pk_bf16_f32 v115, v115, v116
	v_cvt_pk_bf16_f32 v116, v122, v119
	v_cvt_pk_bf16_f32 v117, v120, v117
	global_store_dwordx4 v[136:137], v[114:117], off offset:256 sc1
	v_max_f32_e32 v70, 0, v70
	v_max_f32_e32 v69, 0, v69
	v_lshlrev_b64 v[114:115], 13, v[172:173]
	v_mul_f32_e32 v116, v106, v106
	v_max_f32_e32 v106, 0, v111
	v_lshl_add_u64 v[114:115], s[0:1], 0, v[114:115]
	v_mul_f32_e32 v106, v106, v106
	v_mul_f32_e32 v111, v107, v107
	v_max_f32_e32 v107, 0, v112
	v_mul_f32_e32 v112, v108, v108
	v_max_f32_e32 v108, 0, v113
	v_lshl_add_u64 v[114:115], v[114:115], 0, v[132:133]
	v_mul_f32_e32 v107, v107, v107
	v_mul_f32_e32 v108, v108, v108
	v_cvt_pk_bf16_f32 v106, v110, v106
	v_cvt_pk_bf16_f32 v107, v107, v108
	v_cvt_pk_bf16_f32 v108, v116, v111
	v_cvt_pk_bf16_f32 v109, v112, v109
	global_store_dwordx4 v[114:115], v[106:109], off sc1
	v_pk_mul_f32 v[56:57], v[56:57], v[142:143] op_sel_hi:[1,0]
	v_mul_f32_e32 v70, v70, v70
	v_mul_f32_e32 v106, v98, v98
	v_max_f32_e32 v98, 0, v103
	v_mul_f32_e32 v103, v99, v99
	v_max_f32_e32 v99, 0, v104
	v_mul_f32_e32 v104, v100, v100
	v_max_f32_e32 v100, 0, v105
	v_mul_f32_e32 v98, v98, v98
	v_mul_f32_e32 v99, v99, v99
	v_mul_f32_e32 v100, v100, v100
	v_cvt_pk_bf16_f32 v98, v102, v98
	v_cvt_pk_bf16_f32 v99, v99, v100
	v_cvt_pk_bf16_f32 v100, v106, v103
	v_cvt_pk_bf16_f32 v101, v104, v101
	global_store_dwordx4 v[114:115], v[98:101], off offset:256 sc1
	v_mul_f32_e32 v69, v69, v69
	v_pk_mul_f32 v[60:61], v[60:61], v[142:143] op_sel_hi:[1,0]
	v_lshlrev_b64 v[98:99], 13, v[170:171]
	v_mul_f32_e32 v100, v90, v90
	v_max_f32_e32 v90, 0, v95
	v_lshl_add_u64 v[98:99], s[0:1], 0, v[98:99]
	v_mul_f32_e32 v90, v90, v90
	v_mul_f32_e32 v95, v91, v91
	v_max_f32_e32 v91, 0, v96
	v_mul_f32_e32 v96, v92, v92
	v_max_f32_e32 v92, 0, v97
	v_lshl_add_u64 v[98:99], v[98:99], 0, v[132:133]
	v_mul_f32_e32 v91, v91, v91
	v_mul_f32_e32 v92, v92, v92
	v_cvt_pk_bf16_f32 v90, v94, v90
	v_cvt_pk_bf16_f32 v91, v91, v92
	v_cvt_pk_bf16_f32 v92, v100, v95
	v_cvt_pk_bf16_f32 v93, v96, v93
	global_store_dwordx4 v[98:99], v[90:93], off sc1
	v_pk_mul_f32 v[58:59], v[58:59], v[142:143] op_sel_hi:[1,0]
	v_max_f32_e32 v56, 0, v56
	v_mul_f32_e32 v90, v82, v82
	v_max_f32_e32 v82, 0, v87
	v_mul_f32_e32 v87, v83, v83
	v_max_f32_e32 v83, 0, v88
	v_mul_f32_e32 v88, v84, v84
	v_max_f32_e32 v84, 0, v89
	v_mul_f32_e32 v82, v82, v82
	v_mul_f32_e32 v83, v83, v83
	v_mul_f32_e32 v84, v84, v84
	v_cvt_pk_bf16_f32 v82, v86, v82
	v_cvt_pk_bf16_f32 v83, v83, v84
	v_cvt_pk_bf16_f32 v84, v90, v87
	v_cvt_pk_bf16_f32 v85, v88, v85
	global_store_dwordx4 v[98:99], v[82:85], off offset:256 sc1
	v_pk_mul_f32 v[62:63], v[62:63], v[142:143] op_sel_hi:[1,0]
	v_max_f32_e32 v57, 0, v57
	v_lshlrev_b64 v[82:83], 13, v[168:169]
	v_mul_f32_e32 v84, v74, v74
	v_max_f32_e32 v74, 0, v79
	v_lshl_add_u64 v[82:83], s[0:1], 0, v[82:83]
	v_mul_f32_e32 v74, v74, v74
	v_mul_f32_e32 v79, v75, v75
	v_max_f32_e32 v75, 0, v80
	v_mul_f32_e32 v80, v76, v76
	v_max_f32_e32 v76, 0, v81
	v_lshl_add_u64 v[82:83], v[82:83], 0, v[132:133]
	v_mul_f32_e32 v75, v75, v75
	v_mul_f32_e32 v76, v76, v76
	v_cvt_pk_bf16_f32 v74, v78, v74
	v_cvt_pk_bf16_f32 v75, v75, v76
	v_cvt_pk_bf16_f32 v76, v84, v79
	v_cvt_pk_bf16_f32 v77, v80, v77
	global_store_dwordx4 v[82:83], v[74:77], off sc1
	v_max_f32_e32 v58, 0, v58
	v_max_f32_e32 v60, 0, v60
	v_mul_f32_e32 v74, v66, v66
	v_max_f32_e32 v66, 0, v71
	v_mul_f32_e32 v71, v67, v67
	v_max_f32_e32 v67, 0, v72
	v_mul_f32_e32 v72, v68, v68
	v_max_f32_e32 v68, 0, v73
	v_mul_f32_e32 v66, v66, v66
	v_mul_f32_e32 v67, v67, v67
	v_mul_f32_e32 v68, v68, v68
	v_cvt_pk_bf16_f32 v66, v70, v66
	v_cvt_pk_bf16_f32 v67, v67, v68
	v_cvt_pk_bf16_f32 v68, v74, v71
	v_cvt_pk_bf16_f32 v69, v72, v69
	global_store_dwordx4 v[82:83], v[66:69], off offset:256 sc1
	v_max_f32_e32 v59, 0, v59
	v_pk_mul_f32 v[50:51], v[50:51], v[142:143] op_sel_hi:[1,0]
	v_lshlrev_b64 v[66:67], 13, v[166:167]
	v_mul_f32_e32 v68, v56, v56
	v_max_f32_e32 v56, 0, v61
	v_lshl_add_u64 v[66:67], s[0:1], 0, v[66:67]
	v_mul_f32_e32 v56, v56, v56
	v_mul_f32_e32 v61, v57, v57
	v_max_f32_e32 v57, 0, v62
	v_mul_f32_e32 v62, v58, v58
	v_max_f32_e32 v58, 0, v63
	v_pk_mul_f32 v[48:49], v[48:49], v[142:143] op_sel_hi:[1,0]
	v_lshl_add_u64 v[66:67], v[66:67], 0, v[132:133]
	v_mul_f32_e32 v60, v60, v60
	v_mul_f32_e32 v57, v57, v57
	v_mul_f32_e32 v58, v58, v58
	v_mul_f32_e32 v59, v59, v59
	v_cvt_pk_bf16_f32 v56, v60, v56
	v_pk_mul_f32 v[54:55], v[54:55], v[142:143] op_sel_hi:[1,0]
	v_pk_mul_f32 v[52:53], v[52:53], v[142:143] op_sel_hi:[1,0]
	v_max_f32_e32 v48, 0, v48
	v_max_f32_e32 v49, 0, v49
	v_max_f32_e32 v50, 0, v50
	v_cvt_pk_bf16_f32 v57, v57, v58
	v_cvt_pk_bf16_f32 v58, v68, v61
	v_cvt_pk_bf16_f32 v59, v62, v59
	global_store_dwordx4 v[66:67], v[56:59], off sc1
	v_max_f32_e32 v52, 0, v52
	v_max_f32_e32 v51, 0, v51
	v_mul_f32_e32 v56, v48, v48
	v_max_f32_e32 v48, 0, v53
	v_mul_f32_e32 v53, v49, v49
	v_max_f32_e32 v49, 0, v54
	v_mul_f32_e32 v54, v50, v50
	v_max_f32_e32 v50, 0, v55
	v_mul_f32_e32 v48, v48, v48
	v_mul_f32_e32 v49, v49, v49
	v_mul_f32_e32 v50, v50, v50
	v_pk_mul_f32 v[40:41], v[40:41], v[138:139] op_sel_hi:[1,0]
	v_mul_f32_e32 v52, v52, v52
	v_mul_f32_e32 v51, v51, v51
	v_cvt_pk_bf16_f32 v48, v52, v48
	v_cvt_pk_bf16_f32 v49, v49, v50
	v_cvt_pk_bf16_f32 v50, v56, v53
	v_pk_mul_f32 v[44:45], v[44:45], v[138:139] op_sel_hi:[1,0]
	v_pk_mul_f32 v[42:43], v[42:43], v[138:139] op_sel_hi:[1,0]
	v_max_f32_e32 v40, 0, v40
	v_cvt_pk_bf16_f32 v51, v54, v51
	global_store_dwordx4 v[66:67], v[48:51], off offset:256 sc1
	v_pk_mul_f32 v[46:47], v[46:47], v[138:139] op_sel_hi:[1,0]
	v_max_f32_e32 v41, 0, v41
	v_lshlrev_b64 v[48:49], 13, v[164:165]
	v_mul_f32_e32 v50, v40, v40
	v_max_f32_e32 v40, 0, v45
	v_max_f32_e32 v42, 0, v42
	v_lshl_add_u64 v[48:49], s[0:1], 0, v[48:49]
	v_max_f32_e32 v44, 0, v44
	v_mul_f32_e32 v40, v40, v40
	v_mul_f32_e32 v45, v41, v41
	v_max_f32_e32 v41, 0, v46
	v_mul_f32_e32 v46, v42, v42
	v_max_f32_e32 v42, 0, v47
	v_max_f32_e32 v43, 0, v43
	v_pk_mul_f32 v[34:35], v[34:35], v[138:139] op_sel_hi:[1,0]
	v_pk_mul_f32 v[32:33], v[32:33], v[138:139] op_sel_hi:[1,0]
	v_lshl_add_u64 v[48:49], v[48:49], 0, v[132:133]
	v_mul_f32_e32 v44, v44, v44
	v_mul_f32_e32 v41, v41, v41
	v_mul_f32_e32 v42, v42, v42
	v_mul_f32_e32 v43, v43, v43
	v_cvt_pk_bf16_f32 v40, v44, v40
	v_pk_mul_f32 v[38:39], v[38:39], v[138:139] op_sel_hi:[1,0]
	v_pk_mul_f32 v[36:37], v[36:37], v[138:139] op_sel_hi:[1,0]
	v_max_f32_e32 v32, 0, v32
	v_max_f32_e32 v33, 0, v33
	v_max_f32_e32 v34, 0, v34
	v_cvt_pk_bf16_f32 v41, v41, v42
	v_cvt_pk_bf16_f32 v42, v50, v45
	v_cvt_pk_bf16_f32 v43, v46, v43
	global_store_dwordx4 v[48:49], v[40:43], off sc1
	v_max_f32_e32 v36, 0, v36
	v_max_f32_e32 v35, 0, v35
	v_mul_f32_e32 v40, v32, v32
	v_max_f32_e32 v32, 0, v37
	v_mul_f32_e32 v37, v33, v33
	v_max_f32_e32 v33, 0, v38
	v_mul_f32_e32 v38, v34, v34
	v_max_f32_e32 v34, 0, v39
	v_mul_f32_e32 v32, v32, v32
	v_mul_f32_e32 v33, v33, v33
	v_mul_f32_e32 v34, v34, v34
	v_pk_mul_f32 v[24:25], v[24:25], v[134:135] op_sel_hi:[1,0]
	v_mul_f32_e32 v36, v36, v36
	v_mul_f32_e32 v35, v35, v35
	v_cvt_pk_bf16_f32 v32, v36, v32
	v_cvt_pk_bf16_f32 v33, v33, v34
	v_cvt_pk_bf16_f32 v34, v40, v37
	v_pk_mul_f32 v[28:29], v[28:29], v[134:135] op_sel_hi:[1,0]
	v_pk_mul_f32 v[26:27], v[26:27], v[134:135] op_sel_hi:[1,0]
	v_max_f32_e32 v24, 0, v24
	v_cvt_pk_bf16_f32 v35, v38, v35
	global_store_dwordx4 v[48:49], v[32:35], off offset:256 sc1
	v_pk_mul_f32 v[30:31], v[30:31], v[134:135] op_sel_hi:[1,0]
	v_max_f32_e32 v25, 0, v25
	v_lshlrev_b64 v[32:33], 13, v[162:163]
	v_mul_f32_e32 v34, v24, v24
	v_max_f32_e32 v24, 0, v29
	v_max_f32_e32 v26, 0, v26
	v_lshl_add_u64 v[32:33], s[0:1], 0, v[32:33]
	v_max_f32_e32 v28, 0, v28
	v_mul_f32_e32 v24, v24, v24
	v_mul_f32_e32 v29, v25, v25
	v_max_f32_e32 v25, 0, v30
	v_mul_f32_e32 v30, v26, v26
	v_max_f32_e32 v26, 0, v31
	v_max_f32_e32 v27, 0, v27
	v_pk_mul_f32 v[18:19], v[18:19], v[134:135] op_sel_hi:[1,0]
	v_pk_mul_f32 v[16:17], v[16:17], v[134:135] op_sel_hi:[1,0]
	v_lshl_add_u64 v[32:33], v[32:33], 0, v[132:133]
	v_mul_f32_e32 v28, v28, v28
	v_mul_f32_e32 v25, v25, v25
	v_mul_f32_e32 v26, v26, v26
	v_mul_f32_e32 v27, v27, v27
	v_cvt_pk_bf16_f32 v24, v28, v24
	v_pk_mul_f32 v[22:23], v[22:23], v[134:135] op_sel_hi:[1,0]
	v_pk_mul_f32 v[20:21], v[20:21], v[134:135] op_sel_hi:[1,0]
	v_max_f32_e32 v16, 0, v16
	v_max_f32_e32 v17, 0, v17
	v_max_f32_e32 v18, 0, v18
	v_cvt_pk_bf16_f32 v25, v25, v26
	v_cvt_pk_bf16_f32 v26, v34, v29
	v_cvt_pk_bf16_f32 v27, v30, v27
	global_store_dwordx4 v[32:33], v[24:27], off sc1
	v_max_f32_e32 v20, 0, v20
	v_max_f32_e32 v19, 0, v19
	v_mul_f32_e32 v24, v16, v16
	v_max_f32_e32 v16, 0, v21
	v_mul_f32_e32 v21, v17, v17
	v_max_f32_e32 v17, 0, v22
	v_mul_f32_e32 v22, v18, v18
	v_max_f32_e32 v18, 0, v23
	v_mul_f32_e32 v16, v16, v16
	v_mul_f32_e32 v17, v17, v17
	v_mul_f32_e32 v18, v18, v18
	v_pk_mul_f32 v[8:9], v[8:9], v[130:131] op_sel_hi:[1,0]
	v_mul_f32_e32 v20, v20, v20
	v_mul_f32_e32 v19, v19, v19
	v_cvt_pk_bf16_f32 v16, v20, v16
	v_cvt_pk_bf16_f32 v17, v17, v18
	v_cvt_pk_bf16_f32 v18, v24, v21
	v_pk_mul_f32 v[12:13], v[12:13], v[130:131] op_sel_hi:[1,0]
	v_pk_mul_f32 v[10:11], v[10:11], v[130:131] op_sel_hi:[1,0]
	v_max_f32_e32 v8, 0, v8
	v_cvt_pk_bf16_f32 v19, v22, v19
	global_store_dwordx4 v[32:33], v[16:19], off offset:256 sc1
	v_pk_mul_f32 v[14:15], v[14:15], v[130:131] op_sel_hi:[1,0]
	v_max_f32_e32 v9, 0, v9
	v_lshlrev_b64 v[16:17], 13, v[160:161]
	v_mul_f32_e32 v18, v8, v8
	v_max_f32_e32 v8, 0, v13
	v_max_f32_e32 v10, 0, v10
	v_lshl_add_u64 v[16:17], s[0:1], 0, v[16:17]
	v_max_f32_e32 v12, 0, v12
	v_mul_f32_e32 v8, v8, v8
	v_mul_f32_e32 v13, v9, v9
	v_max_f32_e32 v9, 0, v14
	v_mul_f32_e32 v14, v10, v10
	v_max_f32_e32 v10, 0, v15
	v_max_f32_e32 v11, 0, v11
	v_pk_mul_f32 v[2:3], v[2:3], v[130:131] op_sel_hi:[1,0]
	v_pk_mul_f32 v[0:1], v[0:1], v[130:131] op_sel_hi:[1,0]
	v_lshl_add_u64 v[16:17], v[16:17], 0, v[132:133]
	v_mul_f32_e32 v12, v12, v12
	v_mul_f32_e32 v9, v9, v9
	v_mul_f32_e32 v10, v10, v10
	v_mul_f32_e32 v11, v11, v11
	v_cvt_pk_bf16_f32 v8, v12, v8
	v_pk_mul_f32 v[6:7], v[6:7], v[130:131] op_sel_hi:[1,0]
	v_pk_mul_f32 v[4:5], v[4:5], v[130:131] op_sel_hi:[1,0]
	v_max_f32_e32 v0, 0, v0
	v_max_f32_e32 v1, 0, v1
	v_max_f32_e32 v2, 0, v2
	v_cvt_pk_bf16_f32 v9, v9, v10
	v_cvt_pk_bf16_f32 v10, v18, v13
	v_cvt_pk_bf16_f32 v11, v14, v11
	global_store_dwordx4 v[16:17], v[8:11], off sc1
	v_max_f32_e32 v3, 0, v3
	v_max_f32_e32 v4, 0, v4
	v_mul_f32_e32 v8, v0, v0
	v_max_f32_e32 v0, 0, v5
	v_mul_f32_e32 v5, v1, v1
	v_max_f32_e32 v1, 0, v6
	v_mul_f32_e32 v6, v2, v2
	v_max_f32_e32 v2, 0, v7
	v_mul_f32_e32 v0, v0, v0
	v_mul_f32_e32 v1, v1, v1
	v_mul_f32_e32 v2, v2, v2
	v_mul_f32_e32 v3, v3, v3
	s_mov_b64 s[0:1], -1
	s_andn2_b64 vcc, exec, s[42:43]
	v_mul_f32_e32 v4, v4, v4
	v_cvt_pk_bf16_f32 v0, v4, v0
	v_cvt_pk_bf16_f32 v1, v1, v2
	v_cvt_pk_bf16_f32 v2, v8, v5
	v_cvt_pk_bf16_f32 v3, v6, v3
	global_store_dwordx4 v[16:17], v[0:3], off offset:256 sc1
	s_branch .Lff1_join
